# SSD chunk loop: tile-DMA wait and barrier moved behind the wave-private prefix scan (counted vmcnt leaves the X^T row loads in flight)
# speedup vs baseline: 1.0022x; 1.0022x over previous
; #define LDS_FENCE() asm volatile("s_waitcnt lgkmcnt(0)" ::: "memory")
;     ...
;         const bf16_t* XT = xT + ((size_t)chunk * 2048 + head * 64 + pb * 32 + r) * 128;
;         asm volatile("s_waitcnt vmcnt(0)" ::: "memory"); __builtin_amdgcn_s_barrier(); asm volatile("" ::: "memory");
;         if (s + 1 < 18) { const int s1 = s + 1; const bool cx1 = s1 < 2; const int c1 = cx1 ? (DIR ? 1 - s1 : s1) : (DIR ? 17 - s1 : s1 - 2);
;             const size_t rn = (size_t)(cx1 ? bl * 2 + c1 : (CGR / 128) + bl * 16 + c1) * 128;
;             nd0 = dt[(rn + lane) * 64 + DIR * 32 + head]; nd1 = dt[(rn + 64 + lane) * 64 + DIR * 32 + head]; }
;         float c0, c1, ctot;
;         if (DIR == 0) { const float p0 = wave_prefix(d0 * a_neg, lane); const float tot0 = __int_as_float(__builtin_amdgcn_readlane(__float_as_int(p0), 63)); const float p1 = wave_prefix(d1 * a_neg, lane) + tot0; c0 = p0; c1 = p1; ctot = __int_as_float(__builtin_amdgcn_readlane(__float_as_int(p1), 63)); }
;         else { const float s1 = wave_suffix(d1 * a_neg, lane); const float tot1 = __int_as_float(__builtin_amdgcn_readlane(__float_as_int(s1), 0)); const float s0 = wave_suffix(d0 * a_neg, lane) + tot1; c0 = s0; c1 = s1; ctot = __int_as_float(__builtin_amdgcn_readlane(__float_as_int(s0), 0)); }
;         cumL[lane] = c0; cumL[lane + 64] = c1; dtL[lane] = d0; dtL[lane + 64] = d1;
;         sclL[lane] = d0 * __expf(ctot - c0); sclL[lane + 64] = d1 * __expf(ctot - c1);
;         LDS_FENCE();
;         float mref[4];
;         if (DIR == 0) { mref[0] = 0.f; mref[1] = cumL[31]; mref[2] = cumL[63]; mref[3] = cumL[95]; }
;         else { mref[0] = cumL[32]; mref[1] = cumL[64]; mref[2] = cumL[96]; mref[3] = 0.f; }
; #pragma unroll
;         for (int ib = 0; ib < 4; ++ib) mref[ib] = __int_as_float(__builtin_amdgcn_readfirstlane(__float_as_int(mref[ib])));
;         if (!is_ctx) {
; #pragma unroll
;             for (int ib = 0; ib < 4; ++ib) { wL[ib * 128 + lane] = d0 * __expf(mref[ib] - c0); wL[ib * 128 + 64 + lane] = d1 * __expf(mref[ib] - c1); }
;             LDS_FENCE();
.LBB0_425:
	s_cmp_lg_u32 s52, 17
	s_cselect_b64 s[80:81], -1, 0
	s_cmp_eq_u32 s52, 17
	s_cbranch_scc1 .LBB0_427
	s_add_i32 s33, s58, s48
	s_cmp_eq_u32 s52, 0
	s_cselect_b32 s54, s39, s33
	s_ashr_i32 s55, s54, 31
	s_lshl_b64 s[54:55], s[54:55], 15
	v_lshl_add_u64 v[66:67], v[112:113], 0, s[54:55]
	v_lshl_add_u64 v[66:67], s[36:37], 2, v[66:67]
	global_load_dword v142, v[66:67], off offset:128
	v_add_co_u32_e32 v66, vcc, 0x4000, v66
	s_nop 1
	v_addc_co_u32_e32 v67, vcc, 0, v67, vcc
	global_load_dword v143, v[66:67], off offset:128
.LBB0_427:
	v_mul_f32_e64 v66, v64, -v141
	ds_bpermute_b32 v67, v111, v66
	s_cmp_lt_u32 s52, 2
	s_cselect_b32 s33, 1, 17
	s_cselect_b32 s53, s39, s49
	s_sub_i32 s33, s33, s52
	s_waitcnt lgkmcnt(0)
	v_fma_f32 v67, v64, -v141, v67
	v_cndmask_b32_e64 v66, v67, v66, s[2:3]
	ds_bpermute_b32 v67, v117, v66
	s_add_i32 s54, s33, s53
	v_mov_b32_e32 v70, s76
	s_ashr_i32 s55, s54, 31
	s_lshl_b64 s[54:55], s[54:55], 19
	s_waitcnt lgkmcnt(0)
	v_add_f32_e32 v67, v66, v67
	v_cndmask_b32_e64 v66, v66, v67, s[4:5]
	ds_bpermute_b32 v67, v158, v66
	s_cmp_gt_u32 s52, 1
	v_lshl_add_u64 v[134:135], v[94:95], 0, s[54:55]
	v_lshlrev_b32_e32 v118, 1, v114
	v_mov_b32_e32 v119, 0
	v_lshl_add_u64 v[118:119], v[134:135], 0, v[118:119]
	global_load_dwordx4 v[176:179], v[118:119], off
	global_load_dwordx4 v[180:183], v[118:119], off offset:32
	global_load_dwordx4 v[184:187], v[118:119], off offset:64
	global_load_dwordx4 v[200:203], v[118:119], off offset:96
	global_load_dwordx4 v[204:207], v[118:119], off offset:128
	global_load_dwordx4 v[188:191], v[118:119], off offset:160
	global_load_dwordx4 v[228:231], v[118:119], off offset:192
	global_load_dwordx4 v[232:235], v[118:119], off offset:224
	s_waitcnt lgkmcnt(0)
	v_add_f32_e32 v67, v66, v67
	v_cndmask_b32_e64 v66, v66, v67, s[6:7]
	ds_bpermute_b32 v67, v159, v66
	s_waitcnt lgkmcnt(0)
	v_add_f32_e32 v67, v66, v67
	v_cndmask_b32_e64 v66, v66, v67, s[8:9]
	ds_bpermute_b32 v67, v160, v66
	s_waitcnt lgkmcnt(0)
	v_add_f32_e32 v67, v66, v67
	v_cndmask_b32_e64 v66, v66, v67, s[10:11]
	ds_bpermute_b32 v67, v161, v66
	s_waitcnt lgkmcnt(0)
	v_add_f32_e32 v67, v66, v67
	v_cndmask_b32_e64 v66, v66, v67, s[12:13]
	v_mul_f32_e64 v67, v65, -v141
	ds_bpermute_b32 v68, v111, v67
	v_readlane_b32 s53, v66, 0
	s_waitcnt lgkmcnt(0)
	v_fma_f32 v68, v65, -v141, v68
	v_cndmask_b32_e64 v67, v68, v67, s[2:3]
	ds_bpermute_b32 v68, v117, v67
	s_waitcnt lgkmcnt(0)
	v_add_f32_e32 v68, v67, v68
	v_cndmask_b32_e64 v67, v67, v68, s[4:5]
	ds_bpermute_b32 v68, v158, v67
	s_waitcnt lgkmcnt(0)
	v_add_f32_e32 v68, v67, v68
	v_cndmask_b32_e64 v67, v67, v68, s[6:7]
	ds_bpermute_b32 v68, v159, v67
	s_waitcnt lgkmcnt(0)
	v_add_f32_e32 v68, v67, v68
	v_cndmask_b32_e64 v67, v67, v68, s[8:9]
	ds_bpermute_b32 v68, v160, v67
	s_waitcnt lgkmcnt(0)
	v_add_f32_e32 v68, v67, v68
	v_cndmask_b32_e64 v67, v67, v68, s[10:11]
	ds_bpermute_b32 v68, v161, v67
	s_waitcnt lgkmcnt(0)
	v_add_f32_e32 v68, v67, v68
	v_cndmask_b32_e64 v67, v67, v68, s[12:13]
	v_add_f32_e32 v67, s53, v67
	ds_write2st64_b32 v162, v67, v66 offset1:1
	ds_write2st64_b32 v162, v65, v64 offset0:2 offset1:3
	v_readlane_b32 s53, v67, 0
	s_nop 1
	v_sub_f32_e32 v68, s53, v67
	v_sub_f32_e32 v69, s53, v66
	v_mul_f32_e32 v68, 0x3fb8aa3b, v68
	v_mul_f32_e32 v69, 0x3fb8aa3b, v69
	v_exp_f32_e32 v68, v68
	v_exp_f32_e32 v69, v69
	v_mul_f32_e32 v68, v65, v68
	v_mul_f32_e32 v69, v64, v69
	ds_write2st64_b32 v162, v68, v69 offset0:4 offset1:5
	s_waitcnt lgkmcnt(0)
	ds_read2_b32 v[68:69], v70 offset0:32 offset1:64
	ds_read_b32 v70, v70 offset:384
	s_waitcnt lgkmcnt(0)
	v_readfirstlane_b32 s54, v68
	v_readfirstlane_b32 s55, v69
	s_waitcnt lgkmcnt(0)
	v_readfirstlane_b32 s96, v70
	s_cbranch_scc0 .Lssd_a_ctx
	v_sub_f32_e32 v68, s54, v67
	v_sub_f32_e32 v69, s54, v66
	v_mul_f32_e32 v68, 0x3fb8aa3b, v68
	v_mul_f32_e32 v69, 0x3fb8aa3b, v69
	v_exp_f32_e32 v68, v68
	v_exp_f32_e32 v69, v69
	s_andn2_b64 vcc, exec, s[30:31]
	s_mov_b32 s62, s40
	v_mul_f32_e32 v68, v65, v68
	v_mul_f32_e32 v69, v64, v69
	ds_write2st64_b32 v162, v68, v69 offset0:6 offset1:7
	v_sub_f32_e32 v68, s55, v67
	v_sub_f32_e32 v69, s55, v66
	v_mul_f32_e32 v68, 0x3fb8aa3b, v68
	v_mul_f32_e32 v69, 0x3fb8aa3b, v69
	v_exp_f32_e32 v68, v68
	v_exp_f32_e32 v69, v69
	v_mov_b32_e32 v80, v213
	s_mov_b32 s63, s93
	v_mul_f32_e32 v68, v65, v68
	v_mul_f32_e32 v69, v64, v69
	ds_write2st64_b32 v162, v68, v69 offset0:8 offset1:9
	v_sub_f32_e32 v68, s96, v67
	v_sub_f32_e32 v69, s96, v66
	v_mul_f32_e32 v68, 0x3fb8aa3b, v68
	v_mul_f32_e32 v69, 0x3fb8aa3b, v69
	v_mul_f32_e64 v67, -v67, s71
	v_mul_f32_e64 v66, -v66, s71
	v_exp_f32_e32 v68, v68
	v_exp_f32_e32 v69, v69
	v_exp_f32_e32 v67, v67
	v_exp_f32_e32 v66, v66
	v_mul_f32_e32 v68, v65, v68
	v_mul_f32_e32 v69, v64, v69
	v_mul_f32_e32 v65, v65, v67
	v_mul_f32_e32 v64, v64, v66
	ds_write2st64_b32 v162, v68, v69 offset0:10 offset1:11
	ds_write2st64_b32 v162, v65, v64 offset0:12 offset1:13
	s_waitcnt lgkmcnt(0)
	s_waitcnt vmcnt(8)
	s_barrier
	s_cbranch_vccnz .LBB0_430

; #define LDS_FENCE() asm volatile("s_waitcnt lgkmcnt(0)" ::: "memory")
;     ...
;         asm volatile("s_waitcnt vmcnt(0)" ::: "memory"); __builtin_amdgcn_s_barrier(); asm volatile("" ::: "memory");
;         if (s + 1 < 18) { const int s1 = s + 1; const bool cx1 = s1 < 2; const int c1 = cx1 ? (DIR ? 1 - s1 : s1) : (DIR ? 17 - s1 : s1 - 2);
;             const size_t rn = (size_t)(cx1 ? bl * 2 + c1 : (CGR / 128) + bl * 16 + c1) * 128;
;             nd0 = dt[(rn + lane) * 64 + DIR * 32 + head]; nd1 = dt[(rn + 64 + lane) * 64 + DIR * 32 + head]; }
;         float c0, c1, ctot;
;         if (DIR == 0) { const float p0 = wave_prefix(d0 * a_neg, lane); const float tot0 = __int_as_float(__builtin_amdgcn_readlane(__float_as_int(p0), 63)); const float p1 = wave_prefix(d1 * a_neg, lane) + tot0; c0 = p0; c1 = p1; ctot = __int_as_float(__builtin_amdgcn_readlane(__float_as_int(p1), 63)); }
;         else { const float s1 = wave_suffix(d1 * a_neg, lane); const float tot1 = __int_as_float(__builtin_amdgcn_readlane(__float_as_int(s1), 0)); const float s0 = wave_suffix(d0 * a_neg, lane) + tot1; c0 = s0; c1 = s1; ctot = __int_as_float(__builtin_amdgcn_readlane(__float_as_int(s0), 0)); }
;         cumL[lane] = c0; cumL[lane + 64] = c1; dtL[lane] = d0; dtL[lane + 64] = d1;
;         sclL[lane] = d0 * __expf(ctot - c0); sclL[lane + 64] = d1 * __expf(ctot - c1);
;         LDS_FENCE();
;         float mref[4];
;         if (DIR == 0) { mref[0] = 0.f; mref[1] = cumL[31]; mref[2] = cumL[63]; mref[3] = cumL[95]; }
;         else { mref[0] = cumL[32]; mref[1] = cumL[64]; mref[2] = cumL[96]; mref[3] = 0.f; }
; #pragma unroll
;         for (int ib = 0; ib < 4; ++ib) mref[ib] = __int_as_float(__builtin_amdgcn_readfirstlane(__float_as_int(mref[ib])));
;         if (!is_ctx) {
.Lssd_a_ctx:
	s_waitcnt vmcnt(0)
	s_barrier
	s_branch .LBB0_441

;     ...
;         const bf16_t* XT = xT + ((size_t)chunk * 2048 + head * 64 + pb * 32 + r) * 128;
;         asm volatile("s_waitcnt vmcnt(0)" ::: "memory"); __builtin_amdgcn_s_barrier(); asm volatile("" ::: "memory");
;         if (s + 1 < 18) { const int s1 = s + 1; const bool cx1 = s1 < 2; const int c1 = cx1 ? (DIR ? 1 - s1 : s1) : (DIR ? 17 - s1 : s1 - 2);
;             const size_t rn = (size_t)(cx1 ? bl * 2 + c1 : (CGR / 128) + bl * 16 + c1) * 128;
;             nd0 = dt[(rn + lane) * 64 + DIR * 32 + head]; nd1 = dt[(rn + 64 + lane) * 64 + DIR * 32 + head]; }
;         float c0, c1, ctot;
;         if (DIR == 0) { const float p0 = wave_prefix(d0 * a_neg, lane); const float tot0 = __int_as_float(__builtin_amdgcn_readlane(__float_as_int(p0), 63)); const float p1 = wave_prefix(d1 * a_neg, lane) + tot0; c0 = p0; c1 = p1; ctot = __int_as_float(__builtin_amdgcn_readlane(__float_as_int(p1), 63)); }
;         else { const float s1 = wave_suffix(d1 * a_neg, lane); const float tot1 = __int_as_float(__builtin_amdgcn_readlane(__float_as_int(s1), 0)); const float s0 = wave_suffix(d0 * a_neg, lane) + tot1; c0 = s0; c1 = s1; ctot = __int_as_float(__builtin_amdgcn_readlane(__float_as_int(s0), 0)); }
;         cumL[lane] = c0; cumL[lane + 64] = c1; dtL[lane] = d0; dtL[lane + 64] = d1;
;         sclL[lane] = d0 * __expf(ctot - c0); sclL[lane + 64] = d1 * __expf(ctot - c1);
;         LDS_FENCE();
;         float mref[4];
;         if (DIR == 0) { mref[0] = 0.f; mref[1] = cumL[31]; mref[2] = cumL[63]; mref[3] = cumL[95]; }
;         else { mref[0] = cumL[32]; mref[1] = cumL[64]; mref[2] = cumL[96]; mref[3] = 0.f; }
; #pragma unroll
;         for (int ib = 0; ib < 4; ++ib) mref[ib] = __int_as_float(__builtin_amdgcn_readfirstlane(__float_as_int(mref[ib])));
;         if (!is_ctx) {
; #pragma unroll
;             for (int ib = 0; ib < 4; ++ib) { wL[ib * 128 + lane] = d0 * __expf(mref[ib] - c0); wL[ib * 128 + 64 + lane] = d1 * __expf(mref[ib] - c1); }
;             LDS_FENCE();
; #pragma unroll 1
;             for (int bidx = wid; bidx < 10; bidx += 8) {
;                 int bi2 = bidx >= 6 ? 3 : bidx >= 3 ? 2 : bidx >= 1 ? 1 : 0; int bj2 = bidx - bi2 * (bi2 + 1) / 2;
;                 const int ibk = DIR ? 3 - bi2 : bi2, jbk = DIR ? 3 - bj2 : bj2;
;                 const unsigned io2 = rowoff + (unsigned)ibk * 8192u, jo2 = rowoff + (unsigned)jbk * 8192u;
.LBB0_447:
	s_cmp_lg_u32 s61, 17
	s_cselect_b64 s[0:1], -1, 0
	s_cmp_eq_u32 s61, 17
	s_cbranch_scc1 .LBB0_449
	v_sub_co_u32_e64 v66, s[52:53], s61, 1
	s_and_b64 s[52:53], s[52:53], exec
	v_readfirstlane_b32 s33, v66
	s_cselect_b32 s33, 1, s33
	s_cselect_b32 s51, s78, s79
	s_add_i32 s52, s51, s33
	s_ashr_i32 s53, s52, 31
	s_lshl_b64 s[52:53], s[52:53], 15
	v_lshl_add_u64 v[66:67], v[112:113], 0, s[52:53]
	v_lshl_add_u64 v[66:67], s[36:37], 2, v[66:67]
	global_load_dword v217, v[66:67], off
	v_add_co_u32_e32 v66, vcc, 0x4000, v66
	s_nop 1
	v_addc_co_u32_e32 v67, vcc, 0, v67, vcc
	global_load_dword v218, v[66:67], off
.LBB0_449:
	v_mul_f32_e64 v66, v64, -v215
	ds_bpermute_b32 v67, v188, v66
	v_mul_f32_e64 v68, v65, -v215
	ds_bpermute_b32 v69, v188, v68
	v_sub_co_u32_e64 v80, s[52:53], s61, 2
	s_waitcnt lgkmcnt(0)
	v_fma_f32 v67, v64, -v215, v67
	v_cndmask_b32_e64 v66, v67, v66, s[16:17]
	v_fma_f32 v69, v65, -v215, v69
	ds_bpermute_b32 v67, v189, v66
	v_cndmask_b32_e64 v68, v69, v68, s[16:17]
	ds_bpermute_b32 v69, v189, v68
	v_cndmask_b32_e64 v70, 0, 1, s[52:53]
	s_and_b64 s[52:53], s[52:53], exec
	s_waitcnt lgkmcnt(0)
	v_add_f32_e32 v67, v66, v67
	v_cndmask_b32_e64 v66, v67, v66, s[18:19]
	s_waitcnt lgkmcnt(0)
	v_add_f32_e32 v69, v68, v69
	ds_bpermute_b32 v67, v190, v66
	v_cndmask_b32_e64 v68, v69, v68, s[18:19]
	ds_bpermute_b32 v69, v190, v68
	v_readfirstlane_b32 s33, v80
	s_cselect_b32 s33, s61, s33
	s_waitcnt lgkmcnt(0)
	v_add_f32_e32 v67, v66, v67
	v_cndmask_b32_e64 v66, v67, v66, s[20:21]
	s_waitcnt lgkmcnt(0)
	v_add_f32_e32 v69, v68, v69
	ds_bpermute_b32 v67, v191, v66
	v_cndmask_b32_e64 v68, v69, v68, s[20:21]
	ds_bpermute_b32 v69, v191, v68
	s_cselect_b32 s51, s78, s79
	s_add_i32 s52, s51, s33
	s_waitcnt lgkmcnt(0)
	v_add_f32_e32 v67, v66, v67
	v_cndmask_b32_e64 v66, v67, v66, s[22:23]
	s_waitcnt lgkmcnt(0)
	v_add_f32_e32 v69, v68, v69
	ds_bpermute_b32 v67, v199, v66
	v_cndmask_b32_e64 v68, v69, v68, s[22:23]
	ds_bpermute_b32 v69, v199, v68
	v_mov_b32_e32 v71, s76
	v_cmp_ne_u32_e32 vcc, 1, v70
	s_waitcnt lgkmcnt(0)
	v_add_f32_e32 v67, v66, v67
	v_cndmask_b32_e64 v66, v67, v66, s[24:25]
	s_waitcnt lgkmcnt(0)
	v_add_f32_e32 v69, v68, v69
	ds_bpermute_b32 v67, v161, v66
	v_cndmask_b32_e64 v68, v69, v68, s[24:25]
	ds_bpermute_b32 v69, v161, v68
	s_ashr_i32 s53, s52, 31
	s_lshl_b64 s[80:81], s[52:53], 19
	s_waitcnt lgkmcnt(0)
	v_add_f32_e32 v67, v66, v67
	v_cndmask_b32_e64 v66, v67, v66, s[12:13]
	s_waitcnt lgkmcnt(0)
	v_add_f32_e32 v67, v68, v69
	v_readlane_b32 s33, v66, 63
	v_cndmask_b32_e64 v67, v67, v68, s[12:13]
	v_lshl_add_u64 v[148:149], v[144:145], 0, s[80:81]
	v_lshlrev_b32_e32 v132, 1, v114
	v_mov_b32_e32 v133, 0
	v_lshl_add_u64 v[132:133], v[148:149], 0, v[132:133]
	global_load_dwordx4 v[176:179], v[132:133], off
	global_load_dwordx4 v[180:183], v[132:133], off offset:32
	global_load_dwordx4 v[184:187], v[132:133], off offset:64
	global_load_dwordx4 v[200:203], v[132:133], off offset:96
	global_load_dwordx4 v[204:207], v[132:133], off offset:128
	global_load_dwordx2 v[234:235], v[132:133], off offset:160
	global_load_dwordx2 v[244:245], v[132:133], off offset:168
	global_load_dwordx2 v[158:159], v[132:133], off offset:192
	global_load_dwordx2 v[110:111], v[132:133], off offset:200
	global_load_dwordx2 v[118:119], v[132:133], off offset:224
	global_load_dwordx2 v[174:175], v[132:133], off offset:232
	v_add_f32_e32 v67, s33, v67
	ds_write2st64_b32 v162, v66, v67 offset1:1
	ds_write2st64_b32 v162, v64, v65 offset0:2 offset1:3
	v_readlane_b32 s51, v67, 63
	s_and_b64 vcc, exec, vcc
	s_nop 0
	v_sub_f32_e32 v68, s51, v66
	v_sub_f32_e32 v69, s51, v67
	v_mul_f32_e32 v68, 0x3fb8aa3b, v68
	v_mul_f32_e32 v69, 0x3fb8aa3b, v69
	v_exp_f32_e32 v68, v68
	v_exp_f32_e32 v69, v69
	v_mul_f32_e32 v68, v64, v68
	v_mul_f32_e32 v69, v65, v69
	ds_write2st64_b32 v162, v68, v69 offset0:4 offset1:5
	s_waitcnt lgkmcnt(0)
	ds_read2_b32 v[68:69], v71 offset0:31 offset1:63
	ds_read_b32 v70, v71 offset:380
	s_waitcnt lgkmcnt(0)
	v_readfirstlane_b32 s52, v68
	v_readfirstlane_b32 s53, v69
	s_waitcnt lgkmcnt(0)
	v_readfirstlane_b32 s54, v70
	s_cbranch_vccz .Lssd_b_ctx
	v_mul_f32_e64 v68, -v66, s71
	v_mul_f32_e64 v69, -v67, s71
	v_exp_f32_e32 v68, v68
	v_exp_f32_e32 v69, v69
	v_sub_f32_e32 v70, s53, v66
	v_mul_f32_e32 v70, 0x3fb8aa3b, v70
	v_mul_f32_e32 v68, v64, v68
	v_mul_f32_e32 v69, v65, v69
	ds_write2st64_b32 v162, v68, v69 offset0:6 offset1:7
	v_sub_f32_e32 v68, s52, v66
	v_sub_f32_e32 v69, s52, v67
	v_mul_f32_e32 v68, 0x3fb8aa3b, v68
	v_mul_f32_e32 v69, 0x3fb8aa3b, v69
	v_exp_f32_e32 v68, v68
	v_exp_f32_e32 v69, v69
	v_sub_f32_e32 v66, s54, v66
	v_mul_f32_e32 v66, 0x3fb8aa3b, v66
	v_mul_f32_e32 v68, v64, v68
	v_mul_f32_e32 v69, v65, v69
	ds_write2st64_b32 v162, v68, v69 offset0:8 offset1:9
	v_sub_f32_e32 v69, s53, v67
	v_sub_f32_e32 v67, s54, v67
	v_mul_f32_e32 v69, 0x3fb8aa3b, v69
	v_mul_f32_e32 v67, 0x3fb8aa3b, v67
	v_exp_f32_e32 v70, v70
	v_exp_f32_e32 v69, v69
	v_exp_f32_e32 v66, v66
	v_exp_f32_e32 v67, v67
	v_mul_f32_e32 v68, v64, v70
	v_mul_f32_e32 v69, v65, v69
	v_mul_f32_e32 v64, v64, v66
	v_mul_f32_e32 v65, v65, v67
	ds_write2st64_b32 v162, v68, v69 offset0:10 offset1:11
	ds_write2st64_b32 v162, v64, v65 offset0:12 offset1:13
	s_waitcnt lgkmcnt(0)
	s_andn2_b64 vcc, exec, s[30:31]
	s_lshl_b32 s33, s93, 13
	v_or3_b32 v81, v115, s33, v103
	v_add_u32_e32 v81, 0x8000, v81
	v_or3_b32 v82, v166, s33, v103
	v_add_u32_e32 v82, 0x8000, v82
	v_or3_b32 v83, v167, s33, v103
	v_add_u32_e32 v83, 0x8000, v83
	v_or3_b32 v84, v168, s33, v103
	v_add_u32_e32 v84, 0x8000, v84
	v_or3_b32 v85, v169, s33, v103
	v_add_u32_e32 v85, 0x8000, v85
	v_or3_b32 v86, v170, s33, v103
	v_add_u32_e32 v86, 0x8000, v86
	v_or3_b32 v87, v171, s33, v103
	v_add_u32_e32 v87, 0x8000, v87
	v_or3_b32 v88, v172, s33, v103
	v_add_u32_e32 v88, 0x8000, v88
	v_lshl_or_b32 v89, s93, 11, v165
	s_mov_b32 s33, s93
	s_waitcnt vmcnt(11)
	s_barrier
	s_cbranch_vccnz .LBB0_452
